# K-loop heads plus attention rescale-skip targets and HGRN back-edge targets aligned to 64 bytes
# baseline (speedup 1.0000x reference)
.LBB0_1427:
	s_waitcnt lgkmcnt(14)
	v_mfma_f32_32x32x16_bf16 v[48:63], v[172:175], v[208:211], v[48:63]
	v_exp_f32_e32 v128, v128
	v_exp_f32_e32 v129, v129
	v_exp_f32_e32 v130, v130
	v_exp_f32_e32 v131, v131
	s_waitcnt lgkmcnt(12)
	v_mfma_f32_32x32x16_bf16 v[32:47], v[172:175], v[96:99], v[32:47]
	v_exp_f32_e32 v132, v132
	v_exp_f32_e32 v133, v133
	v_exp_f32_e32 v134, v134
	v_exp_f32_e32 v135, v135
	v_add_u32_e32 v0, s50, v240
	ds_read_b128 v[92:95], v0
	ds_read_b128 v[200:203], v0 offset:512
	s_waitcnt lgkmcnt(12)
	v_mfma_f32_32x32x16_bf16 v[48:63], v[164:167], v[2:5], v[48:63]
	v_exp_f32_e32 v136, v136
	v_exp_f32_e32 v137, v137
	v_exp_f32_e32 v138, v138
	v_exp_f32_e32 v139, v139
	ds_read_b128 v[204:207], v0 offset:2048
	ds_read_b128 v[196:199], v0 offset:2560
	s_waitcnt lgkmcnt(12)
	v_mfma_f32_32x32x16_bf16 v[32:47], v[164:167], v[6:9], v[32:47]
	v_exp_f32_e32 v140, v140
	v_exp_f32_e32 v141, v141
	v_exp_f32_e32 v142, v142
	v_exp_f32_e32 v143, v143
	ds_read_b128 v[192:195], v0 offset:4096
	ds_read_b128 v[188:191], v0 offset:4608
	s_waitcnt lgkmcnt(12)
	v_mfma_f32_32x32x16_bf16 v[48:63], v[156:159], v[10:13], v[48:63]
	v_exp_f32_e32 v112, v112
	v_exp_f32_e32 v113, v113
	v_exp_f32_e32 v114, v114
	v_exp_f32_e32 v115, v115
	ds_read_b128 v[184:187], v0 offset:6144
	ds_read_b128 v[180:183], v0 offset:6656
	s_waitcnt lgkmcnt(12)
	v_mfma_f32_32x32x16_bf16 v[32:47], v[156:159], v[80:83], v[32:47]
	v_exp_f32_e32 v116, v116
	v_exp_f32_e32 v117, v117
	v_exp_f32_e32 v118, v118
	v_exp_f32_e32 v119, v119
	s_waitcnt lgkmcnt(10)
	v_mfma_f32_32x32x16_bf16 v[48:63], v[148:151], v[84:87], v[48:63]
	v_exp_f32_e32 v120, v120
	v_exp_f32_e32 v121, v121
	v_exp_f32_e32 v122, v122
	v_exp_f32_e32 v123, v123
	s_waitcnt lgkmcnt(8)
	v_mfma_f32_32x32x16_bf16 v[32:47], v[148:151], v[88:91], v[32:47]
	v_exp_f32_e32 v124, v124
	v_exp_f32_e32 v125, v125
	v_exp_f32_e32 v126, v126
	v_exp_f32_e32 v127, v127
	s_waitcnt vmcnt(2) lgkmcnt(0)
	s_barrier
	s_andn2_b64 vcc, exec, s[0:1]
	v_add_u32_e32 v0, s59, v242
	s_cbranch_vccnz .LBB0_1429
	s_waitcnt lgkmcnt(0)
	ds_read_b128 v[2:5], v0 offset:49248
	ds_read_b128 v[6:9], v0 offset:49216
	ds_read_b128 v[10:13], v0 offset:49184
	ds_read_b128 v[80:83], v0 offset:49152
	s_waitcnt lgkmcnt(3)
	v_pk_mul_f32 v[60:61], v[60:61], v[2:3]
	s_waitcnt lgkmcnt(2)
	v_pk_mul_f32 v[56:57], v[56:57], v[6:7]
	s_waitcnt lgkmcnt(1)
	v_pk_mul_f32 v[52:53], v[52:53], v[10:11]
	v_pk_mul_f32 v[62:63], v[62:63], v[4:5]
	v_pk_mul_f32 v[58:59], v[58:59], v[8:9]
	v_pk_mul_f32 v[54:55], v[54:55], v[12:13]
	s_waitcnt lgkmcnt(0)
	v_pk_mul_f32 v[50:51], v[50:51], v[82:83]
	v_pk_mul_f32 v[48:49], v[48:49], v[80:81]
	v_pk_mul_f32 v[44:45], v[44:45], v[2:3]
	v_pk_mul_f32 v[40:41], v[40:41], v[6:7]
	v_pk_mul_f32 v[36:37], v[36:37], v[10:11]
	v_pk_mul_f32 v[46:47], v[46:47], v[4:5]
	v_pk_mul_f32 v[42:43], v[42:43], v[8:9]
	v_pk_mul_f32 v[38:39], v[38:39], v[12:13]
	v_pk_mul_f32 v[34:35], v[34:35], v[82:83]
	v_pk_mul_f32 v[32:33], v[32:33], v[80:81]
	.p2align	6

.LBB0_1430:
	s_waitcnt lgkmcnt(14)
	v_mfma_f32_32x32x16_bf16 v[48:63], v[172:175], v[176:179], v[48:63]
	v_exp_f32_e32 v96, v96
	v_exp_f32_e32 v97, v97
	v_exp_f32_e32 v98, v98
	v_exp_f32_e32 v99, v99
	s_waitcnt lgkmcnt(12)
	v_mfma_f32_32x32x16_bf16 v[32:47], v[172:175], v[128:131], v[32:47]
	v_exp_f32_e32 v100, v100
	v_exp_f32_e32 v101, v101
	v_exp_f32_e32 v102, v102
	v_exp_f32_e32 v103, v103
	v_add_u32_e32 v14, s73, v240
	ds_read_b128 v[204:207], v14
	ds_read_b128 v[200:203], v14 offset:512
	s_waitcnt lgkmcnt(12)
	v_mfma_f32_32x32x16_bf16 v[48:63], v[164:167], v[2:5], v[48:63]
	v_exp_f32_e32 v104, v104
	v_exp_f32_e32 v105, v105
	v_exp_f32_e32 v106, v106
	v_exp_f32_e32 v107, v107
	ds_read_b128 v[196:199], v14 offset:2048
	ds_read_b128 v[192:195], v14 offset:2560
	s_waitcnt lgkmcnt(12)
	v_mfma_f32_32x32x16_bf16 v[32:47], v[164:167], v[6:9], v[32:47]
	v_exp_f32_e32 v108, v108
	v_exp_f32_e32 v109, v109
	v_exp_f32_e32 v110, v110
	v_exp_f32_e32 v111, v111
	ds_read_b128 v[188:191], v14 offset:4096
	ds_read_b128 v[184:187], v14 offset:4608
	s_waitcnt lgkmcnt(12)
	v_mfma_f32_32x32x16_bf16 v[48:63], v[156:159], v[10:13], v[48:63]
	v_exp_f32_e32 v80, v80
	v_exp_f32_e32 v81, v81
	v_exp_f32_e32 v82, v82
	v_exp_f32_e32 v83, v83
	ds_read_b128 v[180:183], v14 offset:6144
	ds_read_b128 v[176:179], v14 offset:6656
	s_waitcnt lgkmcnt(12)
	v_mfma_f32_32x32x16_bf16 v[32:47], v[156:159], v[112:115], v[32:47]
	v_exp_f32_e32 v84, v84
	v_exp_f32_e32 v85, v85
	v_exp_f32_e32 v86, v86
	v_exp_f32_e32 v87, v87
	s_waitcnt lgkmcnt(10)
	v_mfma_f32_32x32x16_bf16 v[48:63], v[148:151], v[116:119], v[48:63]
	v_exp_f32_e32 v88, v88
	v_exp_f32_e32 v89, v89
	v_exp_f32_e32 v90, v90
	v_exp_f32_e32 v91, v91
	s_waitcnt lgkmcnt(8)
	v_mfma_f32_32x32x16_bf16 v[32:47], v[148:151], v[120:123], v[32:47]
	v_exp_f32_e32 v92, v92
	v_exp_f32_e32 v93, v93
	v_exp_f32_e32 v94, v94
	v_exp_f32_e32 v95, v95
	s_waitcnt vmcnt(2) lgkmcnt(0)
	s_barrier
	s_andn2_b64 vcc, exec, s[0:1]
	s_cbranch_vccnz .LBB0_1432
	s_waitcnt lgkmcnt(0)
	ds_read_b128 v[2:5], v0 offset:49248
	ds_read_b128 v[6:9], v0 offset:49216
	ds_read_b128 v[10:13], v0 offset:49184
	ds_read_b128 v[112:115], v0 offset:49152
	s_waitcnt lgkmcnt(3)
	v_pk_mul_f32 v[60:61], v[60:61], v[2:3]
	s_waitcnt lgkmcnt(2)
	v_pk_mul_f32 v[56:57], v[56:57], v[6:7]
	s_waitcnt lgkmcnt(1)
	v_pk_mul_f32 v[52:53], v[52:53], v[10:11]
	v_pk_mul_f32 v[62:63], v[62:63], v[4:5]
	v_pk_mul_f32 v[58:59], v[58:59], v[8:9]
	v_pk_mul_f32 v[54:55], v[54:55], v[12:13]
	s_waitcnt lgkmcnt(0)
	v_pk_mul_f32 v[50:51], v[50:51], v[114:115]
	v_pk_mul_f32 v[48:49], v[48:49], v[112:113]
	v_pk_mul_f32 v[44:45], v[44:45], v[2:3]
	v_pk_mul_f32 v[40:41], v[40:41], v[6:7]
	v_pk_mul_f32 v[36:37], v[36:37], v[10:11]
	v_pk_mul_f32 v[46:47], v[46:47], v[4:5]
	v_pk_mul_f32 v[42:43], v[42:43], v[8:9]
	v_pk_mul_f32 v[38:39], v[38:39], v[12:13]
	v_pk_mul_f32 v[34:35], v[34:35], v[114:115]
	v_pk_mul_f32 v[32:33], v[32:33], v[112:113]
	.p2align	6
